# P5 epilogue: a5 (bf16) tile written with 16-byte stores via v_permlane16_swap row pairing instead of 32 dwordx2 stores per lane per tile
# baseline (speedup 1.0000x reference)
; __device__ __forceinline__ unsigned cvt_pk_bf16(float lo, float hi) { unsigned r; asm volatile("v_cvt_pk_bf16_f32 %0, %1, %2" : "=v"(r) : "v"(lo), "v"(hi)); return r; }
;     __device__ __forceinline__ void operator()(const f32x4 (&acc)[2][2][4][2], const Unit& u, int wr, int wc, int fr, int fq) const {
;         const int row0 = u.pm * BM + wr * 64 + fr, col0 = u.pn * BM + wc * 32 + 4 * fq;
; #pragma unroll
;         for (int ai = 0; ai < 2; ++ai)
; #pragma unroll
;             for (int m = 0; m < 4; ++m) { const int row = row0 + ai * HALF + m * 16; const size_t ro = (size_t)row * 2048 + col0; float ss = 0.f;
; #pragma unroll
;                 for (int bj = 0; bj < 2; ++bj)
; #pragma unroll
;                     for (int n = 0; n < 2; ++n) { const size_t off = ro + bj * HALF + n * 16; const f32x4 hv = *(const f32x4*)(R + off) + acc[ai][bj][m][n];
;                         *(f32x4*)(H + off) = hv; ss += (hv[0] * hv[0] + hv[1] * hv[1]) + (hv[2] * hv[2] + hv[3] * hv[3]);
;                         if (WITH_A5) { const f32x4 gv = *(const f32x4*)(gm + col0 + bj * HALF + n * 16); u32x2 w; w.x = cvt_pk_bf16(hv[0] * gv[0], hv[1] * gv[1]); w.y = cvt_pk_bf16(hv[2] * gv[2], hv[3] * gv[3]); *(u32x2*)(a5 + off) = w; } }
;                 ss += __shfl_xor(ss, 16); ss += __shfl_xor(ss, 32);
;                 if (fq == 0) atomicAdd(rowss + row, ss); }
.LBB0_736:
	v_lshlrev_b32_e32 v222, 13, v146
	v_lshl_add_u32 v222, v148, 2, v222
	v_lshlrev_b32_e32 v153, 2, v146
	v_lshrrev_b32_e32 v223, 1, v222
	v_bfe_u32 v140, v152, 4, 1
	v_mul_u32_u24_e32 v140, 24, v140
	v_add_u32_e32 v223, v223, v140
	v_lshlrev_b32_e32 v154, 2, v148
	v_xor_b32_e32 v144, 16, v152
	v_xor_b32_e32 v145, 32, v152
	v_lshlrev_b32_e32 v144, 2, v144
	v_lshlrev_b32_e32 v145, 2, v145
	v_readlane_b32 s52, v234, 5
	v_readlane_b32 s53, v234, 6
	v_readlane_b32 s60, v234, 31
	v_readlane_b32 s61, v234, 32
	s_lshl_b32 s62, s2, 21
	s_lshl_b32 s63, s26, 10
	s_add_u32 s62, s62, s63
	s_nop 1
	s_add_u32 s52, s52, s62
	s_addc_u32 s53, s53, 0
	s_add_u32 s54, s86, s62
	s_addc_u32 s55, s87, 0
	s_add_u32 s60, s60, s63
	s_addc_u32 s61, s61, 0
	s_lshr_b32 s63, s62, 1
	s_add_u32 s56, s10, s63
	s_addc_u32 s57, s11, 0
	s_lshl_b32 s63, s2, 10
	s_add_u32 s58, s12, s63
	s_addc_u32 s59, s13, 0
	global_load_dwordx4 v[158:161], v154, s[60:61]
	global_load_dwordx4 v[162:165], v154, s[60:61] offset:64
	global_load_dwordx4 v[166:169], v154, s[60:61] offset:512
	global_load_dwordx4 v[170:173], v154, s[60:61] offset:576
	global_load_dwordx4 v[174:177], v222, s[52:53]
	global_load_dwordx4 v[178:181], v222, s[52:53] offset:64
	global_load_dwordx4 v[182:185], v222, s[52:53] offset:512
	global_load_dwordx4 v[186:189], v222, s[52:53] offset:576
	s_add_u32 s52, s52, 0x20000
	s_addc_u32 s53, s53, 0
	global_load_dwordx4 v[190:193], v222, s[52:53]
	global_load_dwordx4 v[194:197], v222, s[52:53] offset:64
	global_load_dwordx4 v[198:201], v222, s[52:53] offset:512
	global_load_dwordx4 v[202:205], v222, s[52:53] offset:576
	s_add_u32 s52, s52, 0x20000
	s_addc_u32 s53, s53, 0
	global_load_dwordx4 v[206:209], v222, s[52:53]
	global_load_dwordx4 v[210:213], v222, s[52:53] offset:64
	global_load_dwordx4 v[214:217], v222, s[52:53] offset:512
	global_load_dwordx4 v[218:221], v222, s[52:53] offset:576
	s_add_u32 s52, s52, 0x20000
	s_addc_u32 s53, s53, 0
	s_waitcnt vmcnt(8)
	v_pk_add_f32 v[124:125], v[124:125], v[174:175]
	v_pk_add_f32 v[126:127], v[126:127], v[176:177]
	v_pk_add_f32 v[120:121], v[120:121], v[178:179]
	v_pk_add_f32 v[122:123], v[122:123], v[180:181]
	v_pk_add_f32 v[116:117], v[116:117], v[182:183]
	v_pk_add_f32 v[118:119], v[118:119], v[184:185]
	v_pk_add_f32 v[112:113], v[112:113], v[186:187]
	v_pk_add_f32 v[114:115], v[114:115], v[188:189]
	global_load_dwordx4 v[174:177], v222, s[52:53]
	global_load_dwordx4 v[178:181], v222, s[52:53] offset:64
	global_load_dwordx4 v[182:185], v222, s[52:53] offset:512
	global_load_dwordx4 v[186:189], v222, s[52:53] offset:576
	s_add_u32 s52, s52, 0xa0000
	s_addc_u32 s53, s53, 0
	global_store_dwordx4 v222, v[124:127], s[54:55]
	global_store_dwordx4 v222, v[120:123], s[54:55] offset:64
	global_store_dwordx4 v222, v[116:119], s[54:55] offset:512
	global_store_dwordx4 v222, v[112:115], s[54:55] offset:576
	s_add_u32 s54, s54, 0x20000
	s_addc_u32 s55, s55, 0
	v_mul_f32_e32 v140, v124, v158
	v_mul_f32_e32 v141, v125, v159
	v_mul_f32_e32 v142, v126, v160
	v_mul_f32_e32 v143, v127, v161
	v_cvt_pk_bf16_f32 v224, v140, v141
	v_cvt_pk_bf16_f32 v225, v142, v143
	v_mul_f32_e32 v140, v120, v162
	v_mul_f32_e32 v141, v121, v163
	v_mul_f32_e32 v142, v122, v164
	v_mul_f32_e32 v143, v123, v165
	v_cvt_pk_bf16_f32 v226, v140, v141
	v_cvt_pk_bf16_f32 v227, v142, v143
	v_mul_f32_e32 v140, v116, v166
	v_mul_f32_e32 v141, v117, v167
	v_mul_f32_e32 v142, v118, v168
	v_mul_f32_e32 v143, v119, v169
	v_cvt_pk_bf16_f32 v228, v140, v141
	v_cvt_pk_bf16_f32 v229, v142, v143
	v_mul_f32_e32 v140, v112, v170
	v_mul_f32_e32 v141, v113, v171
	v_mul_f32_e32 v142, v114, v172
	v_mul_f32_e32 v143, v115, v173
	v_cvt_pk_bf16_f32 v230, v140, v141
	v_cvt_pk_bf16_f32 v231, v142, v143
	s_nop 1
	v_permlane16_swap_b32 v224, v226
	v_permlane16_swap_b32 v225, v227
	global_store_dwordx4 v223, v[224:227], s[56:57]
	v_permlane16_swap_b32 v228, v230
	v_permlane16_swap_b32 v229, v231
	global_store_dwordx4 v223, v[228:231], s[56:57] offset:256
	s_add_u32 s56, s56, 0x10000
	s_addc_u32 s57, s57, 0
	v_mul_f32_e32 v140, v125, v125
	v_mul_f32_e32 v141, v127, v127
	v_fmac_f32_e32 v140, v124, v124
	v_fmac_f32_e32 v141, v126, v126
	v_add_f32_e32 v142, v140, v141
	v_mul_f32_e32 v140, v121, v121
	v_mul_f32_e32 v141, v123, v123
	v_fmac_f32_e32 v140, v120, v120
	v_fmac_f32_e32 v141, v122, v122
	v_add_f32_e32 v140, v140, v141
	v_add_f32_e32 v142, v142, v140
	v_mul_f32_e32 v140, v117, v117
	v_mul_f32_e32 v141, v119, v119
	v_fmac_f32_e32 v140, v116, v116
	v_fmac_f32_e32 v141, v118, v118
	v_add_f32_e32 v140, v140, v141
	v_add_f32_e32 v142, v142, v140
	v_mul_f32_e32 v140, v113, v113
	v_mul_f32_e32 v141, v115, v115
	v_fmac_f32_e32 v140, v112, v112
	v_fmac_f32_e32 v141, v114, v114
	v_add_f32_e32 v140, v140, v141
	v_add_f32_e32 v142, v142, v140
	v_mov_b32_e32 v112, v142
	s_waitcnt vmcnt(14)
; __device__ __forceinline__ unsigned cvt_pk_bf16(float lo, float hi) { unsigned r; asm volatile("v_cvt_pk_bf16_f32 %0, %1, %2" : "=v"(r) : "v"(lo), "v"(hi)); return r; }
;     __device__ __forceinline__ void operator()(const f32x4 (&acc)[2][2][4][2], const Unit& u, int wr, int wc, int fr, int fq) const {
;     ...
;             for (int m = 0; m < 4; ++m) { const int row = row0 + ai * HALF + m * 16; const size_t ro = (size_t)row * 2048 + col0; float ss = 0.f;
; #pragma unroll
;                 for (int bj = 0; bj < 2; ++bj)
; #pragma unroll
;                     for (int n = 0; n < 2; ++n) { const size_t off = ro + bj * HALF + n * 16; const f32x4 hv = *(const f32x4*)(R + off) + acc[ai][bj][m][n];
;                         *(f32x4*)(H + off) = hv; ss += (hv[0] * hv[0] + hv[1] * hv[1]) + (hv[2] * hv[2] + hv[3] * hv[3]);
;                         if (WITH_A5) { const f32x4 gv = *(const f32x4*)(gm + col0 + bj * HALF + n * 16); u32x2 w; w.x = cvt_pk_bf16(hv[0] * gv[0], hv[1] * gv[1]); w.y = cvt_pk_bf16(hv[2] * gv[2], hv[3] * gv[3]); *(u32x2*)(a5 + off) = w; } }
;                 ss += __shfl_xor(ss, 16); ss += __shfl_xor(ss, 32);
;                 if (fq == 0) atomicAdd(rowss + row, ss); }
	v_pk_add_f32 v[108:109], v[108:109], v[190:191]
	v_pk_add_f32 v[110:111], v[110:111], v[192:193]
	v_pk_add_f32 v[104:105], v[104:105], v[194:195]
	v_pk_add_f32 v[106:107], v[106:107], v[196:197]
	v_pk_add_f32 v[100:101], v[100:101], v[198:199]
	v_pk_add_f32 v[102:103], v[102:103], v[200:201]
	v_pk_add_f32 v[96:97], v[96:97], v[202:203]
	v_pk_add_f32 v[98:99], v[98:99], v[204:205]
	global_load_dwordx4 v[190:193], v222, s[52:53]
	global_load_dwordx4 v[194:197], v222, s[52:53] offset:64
	global_load_dwordx4 v[198:201], v222, s[52:53] offset:512
	global_load_dwordx4 v[202:205], v222, s[52:53] offset:576
	s_add_u32 s52, s52, 0x20000
	s_addc_u32 s53, s53, 0
	global_store_dwordx4 v222, v[108:111], s[54:55]
	global_store_dwordx4 v222, v[104:107], s[54:55] offset:64
	global_store_dwordx4 v222, v[100:103], s[54:55] offset:512
	global_store_dwordx4 v222, v[96:99], s[54:55] offset:576
	s_add_u32 s54, s54, 0x20000
	s_addc_u32 s55, s55, 0
	v_mul_f32_e32 v140, v108, v158
	v_mul_f32_e32 v141, v109, v159
	v_mul_f32_e32 v142, v110, v160
	v_mul_f32_e32 v143, v111, v161
	v_cvt_pk_bf16_f32 v224, v140, v141
	v_cvt_pk_bf16_f32 v225, v142, v143
	v_mul_f32_e32 v140, v104, v162
	v_mul_f32_e32 v141, v105, v163
	v_mul_f32_e32 v142, v106, v164
	v_mul_f32_e32 v143, v107, v165
	v_cvt_pk_bf16_f32 v226, v140, v141
	v_cvt_pk_bf16_f32 v227, v142, v143
	v_mul_f32_e32 v140, v100, v166
	v_mul_f32_e32 v141, v101, v167
	v_mul_f32_e32 v142, v102, v168
	v_mul_f32_e32 v143, v103, v169
	v_cvt_pk_bf16_f32 v228, v140, v141
	v_cvt_pk_bf16_f32 v229, v142, v143
	v_mul_f32_e32 v140, v96, v170
	v_mul_f32_e32 v141, v97, v171
	v_mul_f32_e32 v142, v98, v172
	v_mul_f32_e32 v143, v99, v173
	v_cvt_pk_bf16_f32 v230, v140, v141
	v_cvt_pk_bf16_f32 v231, v142, v143
	s_nop 1
	v_permlane16_swap_b32 v224, v226
	v_permlane16_swap_b32 v225, v227
	global_store_dwordx4 v223, v[224:227], s[56:57]
	v_permlane16_swap_b32 v228, v230
	v_permlane16_swap_b32 v229, v231
	global_store_dwordx4 v223, v[228:231], s[56:57] offset:256
	s_add_u32 s56, s56, 0x10000
	s_addc_u32 s57, s57, 0
	v_mul_f32_e32 v140, v109, v109
	v_mul_f32_e32 v141, v111, v111
	v_fmac_f32_e32 v140, v108, v108
	v_fmac_f32_e32 v141, v110, v110
	v_add_f32_e32 v142, v140, v141
	v_mul_f32_e32 v140, v105, v105
	v_mul_f32_e32 v141, v107, v107
	v_fmac_f32_e32 v140, v104, v104
	v_fmac_f32_e32 v141, v106, v106
	v_add_f32_e32 v140, v140, v141
	v_add_f32_e32 v142, v142, v140
	v_mul_f32_e32 v140, v101, v101
	v_mul_f32_e32 v141, v103, v103
	v_fmac_f32_e32 v140, v100, v100
	v_fmac_f32_e32 v141, v102, v102
	v_add_f32_e32 v140, v140, v141
	v_add_f32_e32 v142, v142, v140
	v_mul_f32_e32 v140, v97, v97
	v_mul_f32_e32 v141, v99, v99
	v_fmac_f32_e32 v140, v96, v96
	v_fmac_f32_e32 v141, v98, v98
	v_add_f32_e32 v140, v140, v141
	v_add_f32_e32 v142, v142, v140
	v_mov_b32_e32 v96, v142
	s_waitcnt vmcnt(20)
	v_pk_add_f32 v[92:93], v[92:93], v[206:207]
	v_pk_add_f32 v[94:95], v[94:95], v[208:209]
	v_pk_add_f32 v[88:89], v[88:89], v[210:211]
	v_pk_add_f32 v[90:91], v[90:91], v[212:213]
	v_pk_add_f32 v[84:85], v[84:85], v[214:215]
	v_pk_add_f32 v[86:87], v[86:87], v[216:217]
	v_pk_add_f32 v[80:81], v[80:81], v[218:219]
	v_pk_add_f32 v[82:83], v[82:83], v[220:221]
	global_load_dwordx4 v[206:209], v222, s[52:53]
	global_load_dwordx4 v[210:213], v222, s[52:53] offset:64
	global_load_dwordx4 v[214:217], v222, s[52:53] offset:512
	global_load_dwordx4 v[218:221], v222, s[52:53] offset:576
	s_add_u32 s52, s52, 0x20000
	s_addc_u32 s53, s53, 0
	global_store_dwordx4 v222, v[92:95], s[54:55]
	global_store_dwordx4 v222, v[88:91], s[54:55] offset:64
	global_store_dwordx4 v222, v[84:87], s[54:55] offset:512
	global_store_dwordx4 v222, v[80:83], s[54:55] offset:576
	s_add_u32 s54, s54, 0x20000
	s_addc_u32 s55, s55, 0
	v_mul_f32_e32 v140, v92, v158
	v_mul_f32_e32 v141, v93, v159
	v_mul_f32_e32 v142, v94, v160
	v_mul_f32_e32 v143, v95, v161
	v_cvt_pk_bf16_f32 v224, v140, v141
	v_cvt_pk_bf16_f32 v225, v142, v143
	v_mul_f32_e32 v140, v88, v162
	v_mul_f32_e32 v141, v89, v163
	v_mul_f32_e32 v142, v90, v164
	v_mul_f32_e32 v143, v91, v165
	v_cvt_pk_bf16_f32 v226, v140, v141
	v_cvt_pk_bf16_f32 v227, v142, v143
	v_mul_f32_e32 v140, v84, v166
	v_mul_f32_e32 v141, v85, v167
	v_mul_f32_e32 v142, v86, v168
	v_mul_f32_e32 v143, v87, v169
	v_cvt_pk_bf16_f32 v228, v140, v141
	v_cvt_pk_bf16_f32 v229, v142, v143
	v_mul_f32_e32 v140, v80, v170
	v_mul_f32_e32 v141, v81, v171
	v_mul_f32_e32 v142, v82, v172
	v_mul_f32_e32 v143, v83, v173
	v_cvt_pk_bf16_f32 v230, v140, v141
	v_cvt_pk_bf16_f32 v231, v142, v143
	s_nop 1
	v_permlane16_swap_b32 v224, v226
	v_permlane16_swap_b32 v225, v227
	global_store_dwordx4 v223, v[224:227], s[56:57]
	v_permlane16_swap_b32 v228, v230
	v_permlane16_swap_b32 v229, v231
	global_store_dwordx4 v223, v[228:231], s[56:57] offset:256
	s_add_u32 s56, s56, 0x10000
	s_addc_u32 s57, s57, 0
	v_mul_f32_e32 v140, v93, v93
	v_mul_f32_e32 v141, v95, v95
	v_fmac_f32_e32 v140, v92, v92
	v_fmac_f32_e32 v141, v94, v94
	v_add_f32_e32 v142, v140, v141
	v_mul_f32_e32 v140, v89, v89
	v_mul_f32_e32 v141, v91, v91
	v_fmac_f32_e32 v140, v88, v88
	v_fmac_f32_e32 v141, v90, v90
	v_add_f32_e32 v140, v140, v141
	v_add_f32_e32 v142, v142, v140
	v_mul_f32_e32 v140, v85, v85
	v_mul_f32_e32 v141, v87, v87
	v_fmac_f32_e32 v140, v84, v84
	v_fmac_f32_e32 v141, v86, v86
	v_add_f32_e32 v140, v140, v141
	v_add_f32_e32 v142, v142, v140
	v_mul_f32_e32 v140, v81, v81
	v_mul_f32_e32 v141, v83, v83
	v_fmac_f32_e32 v140, v80, v80
	v_fmac_f32_e32 v141, v82, v82
	v_add_f32_e32 v140, v140, v141
	v_add_f32_e32 v142, v142, v140
	v_mov_b32_e32 v80, v142
	s_waitcnt vmcnt(26)
; __device__ __forceinline__ unsigned cvt_pk_bf16(float lo, float hi) { unsigned r; asm volatile("v_cvt_pk_bf16_f32 %0, %1, %2" : "=v"(r) : "v"(lo), "v"(hi)); return r; }
;     __device__ __forceinline__ void operator()(const f32x4 (&acc)[2][2][4][2], const Unit& u, int wr, int wc, int fr, int fq) const {
;     ...
;             for (int m = 0; m < 4; ++m) { const int row = row0 + ai * HALF + m * 16; const size_t ro = (size_t)row * 2048 + col0; float ss = 0.f;
; #pragma unroll
;                 for (int bj = 0; bj < 2; ++bj)
; #pragma unroll
;                     for (int n = 0; n < 2; ++n) { const size_t off = ro + bj * HALF + n * 16; const f32x4 hv = *(const f32x4*)(R + off) + acc[ai][bj][m][n];
;                         *(f32x4*)(H + off) = hv; ss += (hv[0] * hv[0] + hv[1] * hv[1]) + (hv[2] * hv[2] + hv[3] * hv[3]);
;                         if (WITH_A5) { const f32x4 gv = *(const f32x4*)(gm + col0 + bj * HALF + n * 16); u32x2 w; w.x = cvt_pk_bf16(hv[0] * gv[0], hv[1] * gv[1]); w.y = cvt_pk_bf16(hv[2] * gv[2], hv[3] * gv[3]); *(u32x2*)(a5 + off) = w; } }
;                 ss += __shfl_xor(ss, 16); ss += __shfl_xor(ss, 32);
;                 if (fq == 0) atomicAdd(rowss + row, ss); }
	v_pk_add_f32 v[76:77], v[76:77], v[174:175]
	v_pk_add_f32 v[78:79], v[78:79], v[176:177]
	v_pk_add_f32 v[72:73], v[72:73], v[178:179]
	v_pk_add_f32 v[74:75], v[74:75], v[180:181]
	v_pk_add_f32 v[68:69], v[68:69], v[182:183]
	v_pk_add_f32 v[70:71], v[70:71], v[184:185]
	v_pk_add_f32 v[64:65], v[64:65], v[186:187]
	v_pk_add_f32 v[66:67], v[66:67], v[188:189]
	global_load_dwordx4 v[174:177], v222, s[52:53]
	global_load_dwordx4 v[178:181], v222, s[52:53] offset:64
	global_load_dwordx4 v[182:185], v222, s[52:53] offset:512
	global_load_dwordx4 v[186:189], v222, s[52:53] offset:576
	s_add_u32 s52, s52, 0x20000
	s_addc_u32 s53, s53, 0
	global_store_dwordx4 v222, v[76:79], s[54:55]
	global_store_dwordx4 v222, v[72:75], s[54:55] offset:64
	global_store_dwordx4 v222, v[68:71], s[54:55] offset:512
	global_store_dwordx4 v222, v[64:67], s[54:55] offset:576
	s_add_u32 s54, s54, 0xa0000
	s_addc_u32 s55, s55, 0
	v_mul_f32_e32 v140, v76, v158
	v_mul_f32_e32 v141, v77, v159
	v_mul_f32_e32 v142, v78, v160
	v_mul_f32_e32 v143, v79, v161
	v_cvt_pk_bf16_f32 v224, v140, v141
	v_cvt_pk_bf16_f32 v225, v142, v143
	v_mul_f32_e32 v140, v72, v162
	v_mul_f32_e32 v141, v73, v163
	v_mul_f32_e32 v142, v74, v164
	v_mul_f32_e32 v143, v75, v165
	v_cvt_pk_bf16_f32 v226, v140, v141
	v_cvt_pk_bf16_f32 v227, v142, v143
	v_mul_f32_e32 v140, v68, v166
	v_mul_f32_e32 v141, v69, v167
	v_mul_f32_e32 v142, v70, v168
	v_mul_f32_e32 v143, v71, v169
	v_cvt_pk_bf16_f32 v228, v140, v141
	v_cvt_pk_bf16_f32 v229, v142, v143
	v_mul_f32_e32 v140, v64, v170
	v_mul_f32_e32 v141, v65, v171
	v_mul_f32_e32 v142, v66, v172
	v_mul_f32_e32 v143, v67, v173
	v_cvt_pk_bf16_f32 v230, v140, v141
	v_cvt_pk_bf16_f32 v231, v142, v143
	s_nop 1
	v_permlane16_swap_b32 v224, v226
	v_permlane16_swap_b32 v225, v227
	global_store_dwordx4 v223, v[224:227], s[56:57]
	v_permlane16_swap_b32 v228, v230
	v_permlane16_swap_b32 v229, v231
	global_store_dwordx4 v223, v[228:231], s[56:57] offset:256
	s_add_u32 s56, s56, 0x50000
	s_addc_u32 s57, s57, 0
	v_mul_f32_e32 v140, v77, v77
	v_mul_f32_e32 v141, v79, v79
	v_fmac_f32_e32 v140, v76, v76
	v_fmac_f32_e32 v141, v78, v78
	v_add_f32_e32 v142, v140, v141
	v_mul_f32_e32 v140, v73, v73
	v_mul_f32_e32 v141, v75, v75
	v_fmac_f32_e32 v140, v72, v72
	v_fmac_f32_e32 v141, v74, v74
	v_add_f32_e32 v140, v140, v141
	v_add_f32_e32 v142, v142, v140
	v_mul_f32_e32 v140, v69, v69
	v_mul_f32_e32 v141, v71, v71
	v_fmac_f32_e32 v140, v68, v68
	v_fmac_f32_e32 v141, v70, v70
	v_add_f32_e32 v140, v140, v141
	v_add_f32_e32 v142, v142, v140
	v_mul_f32_e32 v140, v65, v65
	v_mul_f32_e32 v141, v67, v67
	v_fmac_f32_e32 v140, v64, v64
	v_fmac_f32_e32 v141, v66, v66
	v_add_f32_e32 v140, v140, v141
	v_add_f32_e32 v142, v142, v140
	v_mov_b32_e32 v64, v142
	s_waitcnt vmcnt(26)
	v_pk_add_f32 v[60:61], v[60:61], v[190:191]
	v_pk_add_f32 v[62:63], v[62:63], v[192:193]
	v_pk_add_f32 v[56:57], v[56:57], v[194:195]
	v_pk_add_f32 v[58:59], v[58:59], v[196:197]
	v_pk_add_f32 v[52:53], v[52:53], v[198:199]
	v_pk_add_f32 v[54:55], v[54:55], v[200:201]
	v_pk_add_f32 v[48:49], v[48:49], v[202:203]
	v_pk_add_f32 v[50:51], v[50:51], v[204:205]
	global_load_dwordx4 v[190:193], v222, s[52:53]
	global_load_dwordx4 v[194:197], v222, s[52:53] offset:64
	global_load_dwordx4 v[198:201], v222, s[52:53] offset:512
	global_load_dwordx4 v[202:205], v222, s[52:53] offset:576
	global_store_dwordx4 v222, v[60:63], s[54:55]
	global_store_dwordx4 v222, v[56:59], s[54:55] offset:64
	global_store_dwordx4 v222, v[52:55], s[54:55] offset:512
	global_store_dwordx4 v222, v[48:51], s[54:55] offset:576
	s_add_u32 s54, s54, 0x20000
	s_addc_u32 s55, s55, 0
	v_mul_f32_e32 v140, v60, v158
	v_mul_f32_e32 v141, v61, v159
	v_mul_f32_e32 v142, v62, v160
	v_mul_f32_e32 v143, v63, v161
	v_cvt_pk_bf16_f32 v224, v140, v141
	v_cvt_pk_bf16_f32 v225, v142, v143
	v_mul_f32_e32 v140, v56, v162
	v_mul_f32_e32 v141, v57, v163
	v_mul_f32_e32 v142, v58, v164
	v_mul_f32_e32 v143, v59, v165
	v_cvt_pk_bf16_f32 v226, v140, v141
	v_cvt_pk_bf16_f32 v227, v142, v143
	v_mul_f32_e32 v140, v52, v166
	v_mul_f32_e32 v141, v53, v167
	v_mul_f32_e32 v142, v54, v168
	v_mul_f32_e32 v143, v55, v169
	v_cvt_pk_bf16_f32 v228, v140, v141
	v_cvt_pk_bf16_f32 v229, v142, v143
	v_mul_f32_e32 v140, v48, v170
	v_mul_f32_e32 v141, v49, v171
	v_mul_f32_e32 v142, v50, v172
	v_mul_f32_e32 v143, v51, v173
	v_cvt_pk_bf16_f32 v230, v140, v141
	v_cvt_pk_bf16_f32 v231, v142, v143
	s_nop 1
	v_permlane16_swap_b32 v224, v226
	v_permlane16_swap_b32 v225, v227
	global_store_dwordx4 v223, v[224:227], s[56:57]
	v_permlane16_swap_b32 v228, v230
	v_permlane16_swap_b32 v229, v231
	global_store_dwordx4 v223, v[228:231], s[56:57] offset:256
	s_add_u32 s56, s56, 0x10000
	s_addc_u32 s57, s57, 0
	v_mul_f32_e32 v140, v61, v61
	v_mul_f32_e32 v141, v63, v63
	v_fmac_f32_e32 v140, v60, v60
	v_fmac_f32_e32 v141, v62, v62
	v_add_f32_e32 v142, v140, v141
	v_mul_f32_e32 v140, v57, v57
	v_mul_f32_e32 v141, v59, v59
	v_fmac_f32_e32 v140, v56, v56
	v_fmac_f32_e32 v141, v58, v58
	v_add_f32_e32 v140, v140, v141
	v_add_f32_e32 v142, v142, v140
	v_mul_f32_e32 v140, v53, v53
	v_mul_f32_e32 v141, v55, v55
	v_fmac_f32_e32 v140, v52, v52
	v_fmac_f32_e32 v141, v54, v54
	v_add_f32_e32 v140, v140, v141
	v_add_f32_e32 v142, v142, v140
	v_mul_f32_e32 v140, v49, v49
	v_mul_f32_e32 v141, v51, v51
	v_fmac_f32_e32 v140, v48, v48
	v_fmac_f32_e32 v141, v50, v50
	v_add_f32_e32 v140, v140, v141
	v_add_f32_e32 v142, v142, v140
	v_mov_b32_e32 v48, v142
	s_waitcnt vmcnt(26)
; __device__ __forceinline__ unsigned cvt_pk_bf16(float lo, float hi) { unsigned r; asm volatile("v_cvt_pk_bf16_f32 %0, %1, %2" : "=v"(r) : "v"(lo), "v"(hi)); return r; }
;     __device__ __forceinline__ void operator()(const f32x4 (&acc)[2][2][4][2], const Unit& u, int wr, int wc, int fr, int fq) const {
;     ...
;             for (int m = 0; m < 4; ++m) { const int row = row0 + ai * HALF + m * 16; const size_t ro = (size_t)row * 2048 + col0; float ss = 0.f;
; #pragma unroll
;                 for (int bj = 0; bj < 2; ++bj)
; #pragma unroll
;                     for (int n = 0; n < 2; ++n) { const size_t off = ro + bj * HALF + n * 16; const f32x4 hv = *(const f32x4*)(R + off) + acc[ai][bj][m][n];
;                         *(f32x4*)(H + off) = hv; ss += (hv[0] * hv[0] + hv[1] * hv[1]) + (hv[2] * hv[2] + hv[3] * hv[3]);
;                         if (WITH_A5) { const f32x4 gv = *(const f32x4*)(gm + col0 + bj * HALF + n * 16); u32x2 w; w.x = cvt_pk_bf16(hv[0] * gv[0], hv[1] * gv[1]); w.y = cvt_pk_bf16(hv[2] * gv[2], hv[3] * gv[3]); *(u32x2*)(a5 + off) = w; } }
;                 ss += __shfl_xor(ss, 16); ss += __shfl_xor(ss, 32);
;                 if (fq == 0) atomicAdd(rowss + row, ss); }
	v_pk_add_f32 v[44:45], v[44:45], v[206:207]
	v_pk_add_f32 v[46:47], v[46:47], v[208:209]
	v_pk_add_f32 v[40:41], v[40:41], v[210:211]
	v_pk_add_f32 v[42:43], v[42:43], v[212:213]
	v_pk_add_f32 v[36:37], v[36:37], v[214:215]
	v_pk_add_f32 v[38:39], v[38:39], v[216:217]
	v_pk_add_f32 v[32:33], v[32:33], v[218:219]
	v_pk_add_f32 v[34:35], v[34:35], v[220:221]
	global_store_dwordx4 v222, v[44:47], s[54:55]
	global_store_dwordx4 v222, v[40:43], s[54:55] offset:64
	global_store_dwordx4 v222, v[36:39], s[54:55] offset:512
	global_store_dwordx4 v222, v[32:35], s[54:55] offset:576
	s_add_u32 s54, s54, 0x20000
	s_addc_u32 s55, s55, 0
	v_mul_f32_e32 v140, v44, v158
	v_mul_f32_e32 v141, v45, v159
	v_mul_f32_e32 v142, v46, v160
	v_mul_f32_e32 v143, v47, v161
	v_cvt_pk_bf16_f32 v224, v140, v141
	v_cvt_pk_bf16_f32 v225, v142, v143
	v_mul_f32_e32 v140, v40, v162
	v_mul_f32_e32 v141, v41, v163
	v_mul_f32_e32 v142, v42, v164
	v_mul_f32_e32 v143, v43, v165
	v_cvt_pk_bf16_f32 v226, v140, v141
	v_cvt_pk_bf16_f32 v227, v142, v143
	v_mul_f32_e32 v140, v36, v166
	v_mul_f32_e32 v141, v37, v167
	v_mul_f32_e32 v142, v38, v168
	v_mul_f32_e32 v143, v39, v169
	v_cvt_pk_bf16_f32 v228, v140, v141
	v_cvt_pk_bf16_f32 v229, v142, v143
	v_mul_f32_e32 v140, v32, v170
	v_mul_f32_e32 v141, v33, v171
	v_mul_f32_e32 v142, v34, v172
	v_mul_f32_e32 v143, v35, v173
	v_cvt_pk_bf16_f32 v230, v140, v141
	v_cvt_pk_bf16_f32 v231, v142, v143
	s_nop 1
	v_permlane16_swap_b32 v224, v226
	v_permlane16_swap_b32 v225, v227
	global_store_dwordx4 v223, v[224:227], s[56:57]
	v_permlane16_swap_b32 v228, v230
	v_permlane16_swap_b32 v229, v231
	global_store_dwordx4 v223, v[228:231], s[56:57] offset:256
	s_add_u32 s56, s56, 0x10000
	s_addc_u32 s57, s57, 0
	v_mul_f32_e32 v140, v45, v45
	v_mul_f32_e32 v141, v47, v47
	v_fmac_f32_e32 v140, v44, v44
	v_fmac_f32_e32 v141, v46, v46
	v_add_f32_e32 v142, v140, v141
	v_mul_f32_e32 v140, v41, v41
	v_mul_f32_e32 v141, v43, v43
	v_fmac_f32_e32 v140, v40, v40
	v_fmac_f32_e32 v141, v42, v42
	v_add_f32_e32 v140, v140, v141
	v_add_f32_e32 v142, v142, v140
	v_mul_f32_e32 v140, v37, v37
	v_mul_f32_e32 v141, v39, v39
	v_fmac_f32_e32 v140, v36, v36
	v_fmac_f32_e32 v141, v38, v38
	v_add_f32_e32 v140, v140, v141
	v_add_f32_e32 v142, v142, v140
	v_mul_f32_e32 v140, v33, v33
	v_mul_f32_e32 v141, v35, v35
	v_fmac_f32_e32 v140, v32, v32
	v_fmac_f32_e32 v141, v34, v34
	v_add_f32_e32 v140, v140, v141
	v_add_f32_e32 v142, v142, v140
	v_mov_b32_e32 v32, v142
	s_waitcnt vmcnt(22)
	v_pk_add_f32 v[28:29], v[28:29], v[174:175]
	v_pk_add_f32 v[30:31], v[30:31], v[176:177]
	v_pk_add_f32 v[24:25], v[24:25], v[178:179]
	v_pk_add_f32 v[26:27], v[26:27], v[180:181]
	v_pk_add_f32 v[20:21], v[20:21], v[182:183]
	v_pk_add_f32 v[22:23], v[22:23], v[184:185]
	v_pk_add_f32 v[16:17], v[16:17], v[186:187]
	v_pk_add_f32 v[18:19], v[18:19], v[188:189]
	global_store_dwordx4 v222, v[28:31], s[54:55]
	global_store_dwordx4 v222, v[24:27], s[54:55] offset:64
	global_store_dwordx4 v222, v[20:23], s[54:55] offset:512
	global_store_dwordx4 v222, v[16:19], s[54:55] offset:576
	s_add_u32 s54, s54, 0x20000
	s_addc_u32 s55, s55, 0
	v_mul_f32_e32 v140, v28, v158
	v_mul_f32_e32 v141, v29, v159
	v_mul_f32_e32 v142, v30, v160
	v_mul_f32_e32 v143, v31, v161
	v_cvt_pk_bf16_f32 v224, v140, v141
	v_cvt_pk_bf16_f32 v225, v142, v143
	v_mul_f32_e32 v140, v24, v162
	v_mul_f32_e32 v141, v25, v163
	v_mul_f32_e32 v142, v26, v164
	v_mul_f32_e32 v143, v27, v165
	v_cvt_pk_bf16_f32 v226, v140, v141
	v_cvt_pk_bf16_f32 v227, v142, v143
	v_mul_f32_e32 v140, v20, v166
	v_mul_f32_e32 v141, v21, v167
	v_mul_f32_e32 v142, v22, v168
	v_mul_f32_e32 v143, v23, v169
	v_cvt_pk_bf16_f32 v228, v140, v141
	v_cvt_pk_bf16_f32 v229, v142, v143
	v_mul_f32_e32 v140, v16, v170
	v_mul_f32_e32 v141, v17, v171
	v_mul_f32_e32 v142, v18, v172
	v_mul_f32_e32 v143, v19, v173
	v_cvt_pk_bf16_f32 v230, v140, v141
	v_cvt_pk_bf16_f32 v231, v142, v143
	s_nop 1
	v_permlane16_swap_b32 v224, v226
	v_permlane16_swap_b32 v225, v227
	global_store_dwordx4 v223, v[224:227], s[56:57]
	v_permlane16_swap_b32 v228, v230
	v_permlane16_swap_b32 v229, v231
	global_store_dwordx4 v223, v[228:231], s[56:57] offset:256
	s_add_u32 s56, s56, 0x10000
	s_addc_u32 s57, s57, 0
	v_mul_f32_e32 v140, v29, v29
	v_mul_f32_e32 v141, v31, v31
	v_fmac_f32_e32 v140, v28, v28
	v_fmac_f32_e32 v141, v30, v30
	v_add_f32_e32 v142, v140, v141
	v_mul_f32_e32 v140, v25, v25
	v_mul_f32_e32 v141, v27, v27
	v_fmac_f32_e32 v140, v24, v24
	v_fmac_f32_e32 v141, v26, v26
	v_add_f32_e32 v140, v140, v141
	v_add_f32_e32 v142, v142, v140
	v_mul_f32_e32 v140, v21, v21
	v_mul_f32_e32 v141, v23, v23
	v_fmac_f32_e32 v140, v20, v20
	v_fmac_f32_e32 v141, v22, v22
	v_add_f32_e32 v140, v140, v141
	v_add_f32_e32 v142, v142, v140
	v_mul_f32_e32 v140, v17, v17
	v_mul_f32_e32 v141, v19, v19
	v_fmac_f32_e32 v140, v16, v16
	v_fmac_f32_e32 v141, v18, v18
	v_add_f32_e32 v140, v140, v141
	v_add_f32_e32 v142, v142, v140
	v_mov_b32_e32 v16, v142
	s_waitcnt vmcnt(18)
; __device__ __forceinline__ unsigned cvt_pk_bf16(float lo, float hi) { unsigned r; asm volatile("v_cvt_pk_bf16_f32 %0, %1, %2" : "=v"(r) : "v"(lo), "v"(hi)); return r; }
;     __device__ __forceinline__ void operator()(const f32x4 (&acc)[2][2][4][2], const Unit& u, int wr, int wc, int fr, int fq) const {
;     ...
;                     for (int n = 0; n < 2; ++n) { const size_t off = ro + bj * HALF + n * 16; const f32x4 hv = *(const f32x4*)(R + off) + acc[ai][bj][m][n];
;                         *(f32x4*)(H + off) = hv; ss += (hv[0] * hv[0] + hv[1] * hv[1]) + (hv[2] * hv[2] + hv[3] * hv[3]);
;                         if (WITH_A5) { const f32x4 gv = *(const f32x4*)(gm + col0 + bj * HALF + n * 16); u32x2 w; w.x = cvt_pk_bf16(hv[0] * gv[0], hv[1] * gv[1]); w.y = cvt_pk_bf16(hv[2] * gv[2], hv[3] * gv[3]); *(u32x2*)(a5 + off) = w; } }
;                 ss += __shfl_xor(ss, 16); ss += __shfl_xor(ss, 32);
;                 if (fq == 0) atomicAdd(rowss + row, ss); }
	v_pk_add_f32 v[12:13], v[12:13], v[190:191]
	v_pk_add_f32 v[14:15], v[14:15], v[192:193]
	v_pk_add_f32 v[8:9], v[8:9], v[194:195]
	v_pk_add_f32 v[10:11], v[10:11], v[196:197]
	v_pk_add_f32 v[4:5], v[4:5], v[198:199]
	v_pk_add_f32 v[6:7], v[6:7], v[200:201]
	v_pk_add_f32 v[0:1], v[0:1], v[202:203]
	v_pk_add_f32 v[2:3], v[2:3], v[204:205]
	global_store_dwordx4 v222, v[12:15], s[54:55]
	global_store_dwordx4 v222, v[8:11], s[54:55] offset:64
	global_store_dwordx4 v222, v[4:7], s[54:55] offset:512
	global_store_dwordx4 v222, v[0:3], s[54:55] offset:576
	v_mul_f32_e32 v140, v12, v158
	v_mul_f32_e32 v141, v13, v159
	v_mul_f32_e32 v142, v14, v160
	v_mul_f32_e32 v143, v15, v161
	v_cvt_pk_bf16_f32 v224, v140, v141
	v_cvt_pk_bf16_f32 v225, v142, v143
	v_mul_f32_e32 v140, v8, v162
	v_mul_f32_e32 v141, v9, v163
	v_mul_f32_e32 v142, v10, v164
	v_mul_f32_e32 v143, v11, v165
	v_cvt_pk_bf16_f32 v226, v140, v141
	v_cvt_pk_bf16_f32 v227, v142, v143
	v_mul_f32_e32 v140, v4, v166
	v_mul_f32_e32 v141, v5, v167
	v_mul_f32_e32 v142, v6, v168
	v_mul_f32_e32 v143, v7, v169
	v_cvt_pk_bf16_f32 v228, v140, v141
	v_cvt_pk_bf16_f32 v229, v142, v143
	v_mul_f32_e32 v140, v0, v170
	v_mul_f32_e32 v141, v1, v171
	v_mul_f32_e32 v142, v2, v172
	v_mul_f32_e32 v143, v3, v173
	v_cvt_pk_bf16_f32 v230, v140, v141
	v_cvt_pk_bf16_f32 v231, v142, v143
	s_nop 1
	v_permlane16_swap_b32 v224, v226
	v_permlane16_swap_b32 v225, v227
	global_store_dwordx4 v223, v[224:227], s[56:57]
	v_permlane16_swap_b32 v228, v230
	v_permlane16_swap_b32 v229, v231
	global_store_dwordx4 v223, v[228:231], s[56:57] offset:256
	v_mul_f32_e32 v140, v13, v13
	v_mul_f32_e32 v141, v15, v15
	v_fmac_f32_e32 v140, v12, v12
	v_fmac_f32_e32 v141, v14, v14
	v_add_f32_e32 v142, v140, v141
	v_mul_f32_e32 v140, v9, v9
	v_mul_f32_e32 v141, v11, v11
	v_fmac_f32_e32 v140, v8, v8
	v_fmac_f32_e32 v141, v10, v10
	v_add_f32_e32 v140, v140, v141
	v_add_f32_e32 v142, v142, v140
	v_mul_f32_e32 v140, v5, v5
	v_mul_f32_e32 v141, v7, v7
	v_fmac_f32_e32 v140, v4, v4
	v_fmac_f32_e32 v141, v6, v6
	v_add_f32_e32 v140, v140, v141
	v_add_f32_e32 v142, v142, v140
	v_mul_f32_e32 v140, v1, v1
	v_mul_f32_e32 v141, v3, v3
	v_fmac_f32_e32 v140, v0, v0
	v_fmac_f32_e32 v141, v2, v2
	v_add_f32_e32 v140, v140, v141
	v_add_f32_e32 v142, v142, v140
	v_mov_b32_e32 v0, v142
	ds_bpermute_b32 v113, v144, v112
	ds_bpermute_b32 v97, v144, v96
	ds_bpermute_b32 v81, v144, v80
	ds_bpermute_b32 v65, v144, v64
	ds_bpermute_b32 v49, v144, v48
	ds_bpermute_b32 v33, v144, v32
	ds_bpermute_b32 v17, v144, v16
	ds_bpermute_b32 v1, v144, v0
	s_waitcnt lgkmcnt(0)
	v_add_f32_e32 v112, v112, v113
	v_add_f32_e32 v96, v96, v97
	v_add_f32_e32 v80, v80, v81
	v_add_f32_e32 v64, v64, v65
	v_add_f32_e32 v48, v48, v49
	v_add_f32_e32 v32, v32, v33
	v_add_f32_e32 v16, v16, v17
	v_add_f32_e32 v0, v0, v1
	ds_bpermute_b32 v113, v145, v112
	ds_bpermute_b32 v97, v145, v96
	ds_bpermute_b32 v81, v145, v80
	ds_bpermute_b32 v65, v145, v64
	ds_bpermute_b32 v49, v145, v48
	ds_bpermute_b32 v33, v145, v32
	ds_bpermute_b32 v17, v145, v16
	ds_bpermute_b32 v1, v145, v0
	s_waitcnt lgkmcnt(0)
	v_add_f32_e32 v112, v112, v113
	v_add_f32_e32 v96, v96, v97
	v_add_f32_e32 v80, v80, v81
	v_add_f32_e32 v64, v64, v65
	v_add_f32_e32 v48, v48, v49
	v_add_f32_e32 v32, v32, v33
	v_add_f32_e32 v16, v16, v17
	v_add_f32_e32 v0, v0, v1
	s_and_saveexec_b64 s[2:3], s[0:1]
	global_atomic_add_f32 v153, v112, s[58:59]
	global_atomic_add_f32 v153, v96, s[58:59] offset:64
	global_atomic_add_f32 v153, v80, s[58:59] offset:128
	global_atomic_add_f32 v153, v64, s[58:59] offset:192
	global_atomic_add_f32 v153, v48, s[58:59] offset:512
	global_atomic_add_f32 v153, v32, s[58:59] offset:576
	global_atomic_add_f32 v153, v16, s[58:59] offset:640
	global_atomic_add_f32 v153, v0, s[58:59] offset:704
	s_or_b64 exec, exec, s[2:3]
	s_andn2_b64 vcc, exec, s[4:5]
	s_mov_b64 s[2:3], -1
	s_cbranch_vccnz .LBB0_725
	s_andn2_b64 vcc, exec, s[8:9]
	s_cbranch_vccnz .LBB0_724
	s_barrier
	s_branch .LBB0_724
